# code placement: attention step loop entry (.Lattn_m2, a taken-branch target) aligned to 64 bytes, on top of v23
# baseline (speedup 1.0000x reference)
.LBB0_655:
	s_add_i32 s10, s73, 1
	s_cmp_lg_u32 s73, 2
	s_cselect_b32 s52, s10, 0
	s_mul_i32 s10, s73, 0x6000
	v_add_u32_e32 v203, s10, v193
	ds_read_b128 v[204:207], v203 offset:32768
	ds_read_b128 v[208:211], v203 offset:45056
	.p2align	6
